# S5 token loops: broadcast operand via op_sel instead of v_mov copies; SSD conv item: previous-token loads issued together
# speedup vs baseline: 1.0006x; 1.0006x over previous
; DI bfr f2bf(float a) { return (bfr)(pk2(a, 0.f) & 0xffffu); }
; template <bool PASSB>
; DI void s5_item(const Params& p, int oi, int witem, float* wl  ) {
;     ...
;     for (int t16 = 0; t16 < 16; ++t16) {
;       const int tt = tb * 16 + t16;
;       float u[16];
; #pragma unroll
;       for (int q = 0; q < 4; ++q) { const f32x4 v = *(const f32x4*)(wl + tt * 16 + q * 4); u[q * 4] = v[0]; u[q * 4 + 1] = v[1]; u[q * 4 + 2] = v[2]; u[q * 4 + 3] = v[3]; }
;       float ar0 = 0.f, ar1 = 0.f, ai0 = 0.f, ai1 = 0.f;
; #pragma unroll
;       for (int h = 0; h < 16; h += 2) { ar0 += bre[h] * u[h]; ar1 += bre[h + 1] * u[h + 1]; ai0 += bim[h] * u[h]; ai1 += bim[h + 1] * u[h + 1]; }
;       const float ar = ar0 + ar1, ai = ai0 + ai1;
;       const float nr = lre * xre - lim * xim + ar, ni = lre * xim + lim * xre + ai;
;       xre = nr; xim = ni;
;       if (PASSB) { xl[t16 * 136 + lane] = f2bf(xre); xl[t16 * 136 + 64 + lane] = f2bf(xim); }
;     }
.LBB0_161:
	s_add_i32 s27, s24, s25
	v_mov_b32_e32 v61, s27
	ds_read_b128 v[66:69], v61
	ds_read_b128 v[70:73], v61 offset:16
	ds_read_b128 v[74:77], v61 offset:32
	ds_read_b128 v[78:81], v61 offset:48
	v_pk_mul_f32 v[82:83], v[58:59], v[54:55] op_sel:[0,1]
	s_waitcnt lgkmcnt(3)
	v_pk_fma_f32 v[84:85], v[20:21], v[66:67], 0 op_sel_hi:[1,0,0]
	v_pk_fma_f32 v[66:67], v[22:23], v[66:67], 0 op_sel:[0,1,0] op_sel_hi:[1,1,0]
	v_pk_fma_f32 v[84:85], v[24:25], v[68:69], v[84:85] op_sel_hi:[1,0,1]
	v_pk_fma_f32 v[66:67], v[26:27], v[68:69], v[66:67] op_sel:[0,1,0]
	s_waitcnt lgkmcnt(2)
	v_pk_fma_f32 v[68:69], v[28:29], v[70:71], v[84:85] op_sel_hi:[1,0,1]
	v_pk_fma_f32 v[66:67], v[30:31], v[70:71], v[66:67] op_sel:[0,1,0]
	v_pk_fma_f32 v[68:69], v[32:33], v[72:73], v[68:69] op_sel_hi:[1,0,1]
	v_pk_fma_f32 v[66:67], v[34:35], v[72:73], v[66:67] op_sel:[0,1,0]
	s_waitcnt lgkmcnt(1)
	v_pk_fma_f32 v[68:69], v[36:37], v[74:75], v[68:69] op_sel_hi:[1,0,1]
	v_pk_fma_f32 v[66:67], v[38:39], v[74:75], v[66:67] op_sel:[0,1,0]
	v_pk_fma_f32 v[68:69], v[40:41], v[76:77], v[68:69] op_sel_hi:[1,0,1]
	v_pk_fma_f32 v[66:67], v[42:43], v[76:77], v[66:67] op_sel:[0,1,0]
	s_waitcnt lgkmcnt(0)
	v_pk_fma_f32 v[68:69], v[44:45], v[78:79], v[68:69] op_sel_hi:[1,0,1]
	v_pk_fma_f32 v[66:67], v[46:47], v[78:79], v[66:67] op_sel:[0,1,0]
	v_pk_fma_f32 v[68:69], v[48:49], v[80:81], v[68:69] op_sel_hi:[1,0,1]
	v_pk_fma_f32 v[66:67], v[50:51], v[80:81], v[66:67] op_sel:[0,1,0]
	s_addk_i32 s25, 0x80
	v_pk_add_f32 v[66:67], v[68:69], v[66:67]
	v_pk_fma_f32 v[68:69], v[52:53], v[54:55], v[82:83] neg_lo:[0,0,1] neg_hi:[0,0,1]
	v_pk_fma_f32 v[54:55], v[52:53], v[54:55], v[82:83] op_sel_hi:[1,0,1]
	s_cmpk_lg_i32 s25, 0x400
	v_mov_b32_e32 v69, v55
	v_pk_add_f32 v[54:55], v[68:69], v[66:67]
	s_nop 0
	v_cvt_pk_bf16_f32 v66, v54, s0
	ds_write_b16 v60, v66
	v_cvt_pk_bf16_f32 v66, v55, s0
	ds_write_b16 v60, v66 offset:128
	ds_read_b128 v[66:69], v61 offset:64
	ds_read_b128 v[70:73], v61 offset:80
	ds_read_b128 v[74:77], v61 offset:96
	ds_read_b128 v[78:81], v61 offset:112
	v_pk_mul_f32 v[82:83], v[58:59], v[54:55] op_sel:[0,1]
	s_waitcnt lgkmcnt(3)
	v_pk_fma_f32 v[84:85], v[20:21], v[66:67], 0 op_sel_hi:[1,0,0]
	v_pk_fma_f32 v[66:67], v[22:23], v[66:67], 0 op_sel:[0,1,0] op_sel_hi:[1,1,0]
	v_pk_fma_f32 v[84:85], v[24:25], v[68:69], v[84:85] op_sel_hi:[1,0,1]
	v_pk_fma_f32 v[66:67], v[26:27], v[68:69], v[66:67] op_sel:[0,1,0]
	s_waitcnt lgkmcnt(2)
	v_pk_fma_f32 v[68:69], v[28:29], v[70:71], v[84:85] op_sel_hi:[1,0,1]
	v_pk_fma_f32 v[66:67], v[30:31], v[70:71], v[66:67] op_sel:[0,1,0]
	v_pk_fma_f32 v[68:69], v[32:33], v[72:73], v[68:69] op_sel_hi:[1,0,1]
	v_pk_fma_f32 v[66:67], v[34:35], v[72:73], v[66:67] op_sel:[0,1,0]
	s_waitcnt lgkmcnt(1)
	v_pk_fma_f32 v[68:69], v[36:37], v[74:75], v[68:69] op_sel_hi:[1,0,1]
	v_pk_fma_f32 v[66:67], v[38:39], v[74:75], v[66:67] op_sel:[0,1,0]
	v_pk_fma_f32 v[68:69], v[40:41], v[76:77], v[68:69] op_sel_hi:[1,0,1]
	v_pk_fma_f32 v[66:67], v[42:43], v[76:77], v[66:67] op_sel:[0,1,0]
	s_waitcnt lgkmcnt(0)
	v_pk_fma_f32 v[68:69], v[44:45], v[78:79], v[68:69] op_sel_hi:[1,0,1]
	v_pk_fma_f32 v[66:67], v[46:47], v[78:79], v[66:67] op_sel:[0,1,0]
	v_pk_fma_f32 v[68:69], v[48:49], v[80:81], v[68:69] op_sel_hi:[1,0,1]
	v_pk_fma_f32 v[66:67], v[50:51], v[80:81], v[66:67] op_sel:[0,1,0]
	s_nop 0
	v_pk_add_f32 v[66:67], v[68:69], v[66:67]
	v_pk_fma_f32 v[68:69], v[52:53], v[54:55], v[82:83] neg_lo:[0,0,1] neg_hi:[0,0,1]
	v_pk_fma_f32 v[54:55], v[52:53], v[54:55], v[82:83] op_sel_hi:[1,0,1]
	s_nop 0
	v_mov_b32_e32 v69, v55
	v_pk_add_f32 v[54:55], v[68:69], v[66:67]
	s_nop 0
	v_cvt_pk_bf16_f32 v61, v54, s0
	ds_write_b16 v60, v61 offset:272
	v_cvt_pk_bf16_f32 v61, v55, s0
	ds_write_b16 v60, v61 offset:400
	v_add_u32_e32 v60, 0x220, v60
	s_cbranch_scc1 .LBB0_161
; #define MFMA16(a, b, c) __builtin_amdgcn_mfma_f32_16x16x32_bf16((a), (b), (c), 0, 0, 0)
; DI u32x2 pk4(const f32x4& v) { u32x2 r = {pk2(v[0], v[1]), pk2(v[2], v[3])}; return r; }
; template <bool PASSB>
; DI void s5_item(const Params& p, int oi, int witem, float* wl  ) {
;     ...
;     if (PASSB) {
;       __builtin_amdgcn_wave_barrier();
;       f32x4 y = {0.f, 0.f, 0.f, 0.f};
; #pragma unroll
;       for (int ks = 0; ks < 4; ++ks) y = MFMA16(cf[ks], *(const bf16x8*)(xl + r16 * 136 + ks * 32 + quad * 8), y);
;       const int t = tb * 16 + r16;
;       const f32x4 uu = *(const f32x4*)(wl + t * 16 + quad * 4);
;       f32x4 o;
; #pragma unroll
;       for (int i = 0; i < 4; ++i) o[i] = gelu_tanh(y[i] + dsk4[i] * uu[i]);
;       *(u32x2*)(yg + (tg0 + t) * 512 + g * 16 + quad * 4) = pk4(o);
;       __builtin_amdgcn_wave_barrier();
;     }
;   }
	ds_read_b128 v[66:69], v64 offset:4096
	ds_read_b128 v[70:73], v64 offset:4160
	v_lshl_or_b32 v176, s3, 4, v62
	v_lshl_add_u32 v60, v176, 6, v63
	s_add_i32 s3, s3, 1
	s_waitcnt lgkmcnt(1)
	v_mfma_f32_16x16x32_bf16 v[66:69], v[0:3], v[66:69], 0
	s_addk_i32 s24, 0x400
	s_cmp_lg_u32 s3, 4
	s_waitcnt lgkmcnt(0)
	v_mfma_f32_16x16x32_bf16 v[66:69], v[4:7], v[70:73], v[66:69]
	ds_read_b128 v[70:73], v64 offset:4224
	s_waitcnt lgkmcnt(0)
	v_mfma_f32_16x16x32_bf16 v[66:69], v[8:11], v[70:73], v[66:69]
	ds_read_b128 v[70:73], v64 offset:4288
	s_waitcnt lgkmcnt(0)
	v_mfma_f32_16x16x32_bf16 v[66:69], v[12:15], v[70:73], v[66:69]
	ds_read_b128 v[70:73], v60
	s_waitcnt lgkmcnt(0)
	s_nop 5
	v_pk_fma_f32 v[66:67], v[16:17], v[70:71], v[66:67]
	v_pk_fma_f32 v[60:61], v[18:19], v[72:73], v[68:69]
	v_mul_f32_e32 v68, 0x3d372713, v66
	v_mul_f32_e32 v69, 0x3d372713, v67
	v_mul_f32_e32 v68, v66, v68
	v_mul_f32_e32 v69, v67, v69
	v_fma_f32 v68, v66, v68, v66
	v_fma_f32 v69, v67, v69, v67
	v_mul_f32_e32 v68, 0x3f4c422a, v68
	v_mul_f32_e32 v69, 0x3f4c422a, v69
	v_add_f32_e32 v68, v68, v68
	v_add_f32_e32 v69, v69, v69
	v_mul_f32_e32 v68, 0x3fb8aa3b, v68
	v_mul_f32_e32 v69, 0x3fb8aa3b, v69
	v_exp_f32_e32 v68, v68
	v_exp_f32_e32 v69, v69
	v_pk_mul_f32 v[66:67], v[66:67], 0.5 op_sel_hi:[1,0]
	v_pk_add_f32 v[68:69], v[68:69], 1.0 op_sel_hi:[1,0]
	s_nop 0
	v_div_scale_f32 v70, s[30:31], v69, v69, 2.0
	v_rcp_f32_e32 v71, v70
	s_nop 0
	v_fma_f32 v72, -v70, v71, 1.0
	v_fmac_f32_e32 v71, v72, v71
	v_div_scale_f32 v72, vcc, 2.0, v69, 2.0
	v_mul_f32_e32 v73, v72, v71
	v_fma_f32 v74, -v70, v73, v72
	v_fmac_f32_e32 v73, v74, v71
	v_fma_f32 v70, -v70, v73, v72
	v_div_fmas_f32 v70, v70, v71, v73
	v_div_fixup_f32 v69, v70, v69, 2.0
	v_div_scale_f32 v70, s[30:31], v68, v68, 2.0
	v_rcp_f32_e32 v71, v70
	s_nop 0
	v_fma_f32 v72, -v70, v71, 1.0
	v_fmac_f32_e32 v71, v72, v71
	v_div_scale_f32 v72, vcc, 2.0, v68, 2.0
	v_mul_f32_e32 v73, v72, v71
	v_fma_f32 v74, -v70, v73, v72
	v_fmac_f32_e32 v73, v74, v71
	v_fma_f32 v70, -v70, v73, v72
	v_div_fmas_f32 v70, v70, v71, v73
	v_div_fixup_f32 v68, v70, v68, 2.0
	v_pk_add_f32 v[68:69], v[68:69], 1.0 op_sel_hi:[1,0] neg_lo:[1,0] neg_hi:[1,0]
	s_nop 0
	v_pk_add_f32 v[68:69], v[68:69], 1.0 op_sel_hi:[1,0]
	s_nop 0
	v_pk_mul_f32 v[66:67], v[66:67], v[68:69]
	v_mul_f32_e32 v68, 0x3d372713, v60
	v_mul_f32_e32 v69, 0x3d372713, v61
	v_mul_f32_e32 v68, v60, v68
	v_mul_f32_e32 v69, v61, v69
	v_fma_f32 v68, v60, v68, v60
	v_fma_f32 v69, v61, v69, v61
	v_mul_f32_e32 v68, 0x3f4c422a, v68
	v_mul_f32_e32 v69, 0x3f4c422a, v69
	v_add_f32_e32 v68, v68, v68
	v_add_f32_e32 v69, v69, v69
	v_mul_f32_e32 v68, 0x3fb8aa3b, v68
	v_mul_f32_e32 v69, 0x3fb8aa3b, v69
	v_exp_f32_e32 v68, v68
	v_exp_f32_e32 v69, v69
	v_pk_mul_f32 v[60:61], v[60:61], 0.5 op_sel_hi:[1,0]
	v_cvt_pk_bf16_f32 v66, v66, v67
	v_pk_add_f32 v[68:69], v[68:69], 1.0 op_sel_hi:[1,0]
	s_nop 0
	v_div_scale_f32 v70, s[30:31], v69, v69, 2.0
	v_rcp_f32_e32 v71, v70
	s_nop 0
	v_fma_f32 v72, -v70, v71, 1.0
	v_fmac_f32_e32 v71, v72, v71
	v_div_scale_f32 v72, vcc, 2.0, v69, 2.0
	v_mul_f32_e32 v73, v72, v71
	v_fma_f32 v74, -v70, v73, v72
	v_fmac_f32_e32 v73, v74, v71
	v_fma_f32 v70, -v70, v73, v72
	v_div_fmas_f32 v70, v70, v71, v73
	v_div_fixup_f32 v69, v70, v69, 2.0
	v_div_scale_f32 v70, s[30:31], v68, v68, 2.0
	v_rcp_f32_e32 v71, v70
	s_nop 0
	v_fma_f32 v72, -v70, v71, 1.0
	v_fmac_f32_e32 v71, v72, v71
	v_div_scale_f32 v72, vcc, 2.0, v68, 2.0
	v_mul_f32_e32 v73, v72, v71
	v_fma_f32 v74, -v70, v73, v72
	v_fmac_f32_e32 v73, v74, v71
	v_fma_f32 v70, -v70, v73, v72
	v_div_fmas_f32 v70, v70, v71, v73
	v_div_fixup_f32 v68, v70, v68, 2.0
	v_pk_add_f32 v[68:69], v[68:69], 1.0 op_sel_hi:[1,0] neg_lo:[1,0] neg_hi:[1,0]
	s_nop 0
	v_pk_add_f32 v[68:69], v[68:69], 1.0 op_sel_hi:[1,0]
	s_nop 0
	v_pk_mul_f32 v[60:61], v[60:61], v[68:69]
	s_nop 0
	v_cvt_pk_bf16_f32 v67, v60, v61
	v_lshl_add_u64 v[60:61], s[4:5], 0, v[176:177]
	v_lshlrev_b64 v[60:61], 10, v[60:61]
	v_lshl_add_u64 v[60:61], v[56:57], 0, v[60:61]
	global_store_dwordx2 v[60:61], v[66:67], off
	s_cbranch_scc1 .LBB0_160
	v_mov_b32_e32 v254, v54
	v_mov_b32_e32 v255, v55
	s_add_i32 s2, s2, s68
	s_cmpk_gt_i32 s2, 0xfff
	s_cbranch_scc0 .LBB0_152

; #define MFMA16(a, b, c) __builtin_amdgcn_mfma_f32_16x16x32_bf16((a), (b), (c), 0, 0, 0)
; DI bfr f2bf(float a) { return (bfr)(pk2(a, 0.f) & 0xffffu); }
; DI u32x2 pk4(const f32x4& v) { u32x2 r = {pk2(v[0], v[1]), pk2(v[2], v[3])}; return r; }
; template <bool PASSB>
; DI void s5_item(const Params& p, int oi, int witem, float* wl  ) {
;     ...
;   for (int tb = 0; tb < 4; ++tb) {
; #pragma unroll 2
;     for (int t16 = 0; t16 < 16; ++t16) {
;       const int tt = tb * 16 + t16;
;       float u[16];
; #pragma unroll
;       for (int q = 0; q < 4; ++q) { const f32x4 v = *(const f32x4*)(wl + tt * 16 + q * 4); u[q * 4] = v[0]; u[q * 4 + 1] = v[1]; u[q * 4 + 2] = v[2]; u[q * 4 + 3] = v[3]; }
;       float ar0 = 0.f, ar1 = 0.f, ai0 = 0.f, ai1 = 0.f;
; #pragma unroll
;       for (int h = 0; h < 16; h += 2) { ar0 += bre[h] * u[h]; ar1 += bre[h + 1] * u[h + 1]; ai0 += bim[h] * u[h]; ai1 += bim[h + 1] * u[h + 1]; }
;       const float ar = ar0 + ar1, ai = ai0 + ai1;
;       const float nr = lre * xre - lim * xim + ar, ni = lre * xim + lim * xre + ai;
;       xre = nr; xim = ni;
;       if (PASSB) { xl[t16 * 136 + lane] = f2bf(xre); xl[t16 * 136 + 64 + lane] = f2bf(xim); }
;     }
;     if (PASSB) {
;       __builtin_amdgcn_wave_barrier();
;       f32x4 y = {0.f, 0.f, 0.f, 0.f};
; #pragma unroll
;       for (int ks = 0; ks < 4; ++ks) y = MFMA16(cf[ks], *(const bf16x8*)(xl + r16 * 136 + ks * 32 + quad * 8), y);
;       const int t = tb * 16 + r16;
;       const f32x4 uu = *(const f32x4*)(wl + t * 16 + quad * 4);
;       f32x4 o;
; #pragma unroll
;       for (int i = 0; i < 4; ++i) o[i] = gelu_tanh(y[i] + dsk4[i] * uu[i]);
;       *(u32x2*)(yg + (tg0 + t) * 512 + g * 16 + quad * 4) = pk4(o);
;       __builtin_amdgcn_wave_barrier();
;     }
;   }
;   if (!PASSB) {
;     float* Sp = S + ((size_t)bgi * 256 + c) * 128;
;     Sp[lane] = xre; Sp[64 + lane] = xim;
;   }
.LBB0_172:
	s_add_i32 s27, s24, s25
	v_mov_b32_e32 v39, s27
	ds_read_b128 v[40:43], v39
	ds_read_b128 v[44:47], v39 offset:16
	ds_read_b128 v[48:51], v39 offset:32
	ds_read_b128 v[52:55], v39 offset:48
	v_pk_mul_f32 v[56:57], v[34:35], v[36:37] op_sel:[0,1]
	s_waitcnt lgkmcnt(3)
	v_pk_fma_f32 v[58:59], v[2:3], v[40:41], 0 op_sel_hi:[1,0,0]
	v_pk_fma_f32 v[40:41], v[4:5], v[40:41], 0 op_sel:[0,1,0] op_sel_hi:[1,1,0]
	v_pk_fma_f32 v[58:59], v[6:7], v[42:43], v[58:59] op_sel_hi:[1,0,1]
	v_pk_fma_f32 v[40:41], v[8:9], v[42:43], v[40:41] op_sel:[0,1,0]
	s_waitcnt lgkmcnt(2)
	v_pk_fma_f32 v[42:43], v[10:11], v[44:45], v[58:59] op_sel_hi:[1,0,1]
	v_pk_fma_f32 v[40:41], v[12:13], v[44:45], v[40:41] op_sel:[0,1,0]
	v_pk_fma_f32 v[42:43], v[14:15], v[46:47], v[42:43] op_sel_hi:[1,0,1]
	v_pk_fma_f32 v[40:41], v[16:17], v[46:47], v[40:41] op_sel:[0,1,0]
	s_waitcnt lgkmcnt(1)
	v_pk_fma_f32 v[42:43], v[18:19], v[48:49], v[42:43] op_sel_hi:[1,0,1]
	v_pk_fma_f32 v[40:41], v[20:21], v[48:49], v[40:41] op_sel:[0,1,0]
	v_pk_fma_f32 v[42:43], v[22:23], v[50:51], v[42:43] op_sel_hi:[1,0,1]
	v_pk_fma_f32 v[40:41], v[24:25], v[50:51], v[40:41] op_sel:[0,1,0]
	s_waitcnt lgkmcnt(0)
	v_pk_fma_f32 v[42:43], v[26:27], v[52:53], v[42:43] op_sel_hi:[1,0,1]
	v_pk_fma_f32 v[40:41], v[28:29], v[52:53], v[40:41] op_sel:[0,1,0]
	v_pk_fma_f32 v[42:43], v[30:31], v[54:55], v[42:43] op_sel_hi:[1,0,1]
	v_pk_fma_f32 v[40:41], v[32:33], v[54:55], v[40:41] op_sel:[0,1,0]
	s_addk_i32 s25, 0x80
	v_pk_add_f32 v[40:41], v[42:43], v[40:41]
	v_pk_fma_f32 v[42:43], v[0:1], v[36:37], v[56:57] neg_lo:[0,0,1] neg_hi:[0,0,1]
	v_pk_fma_f32 v[36:37], v[0:1], v[36:37], v[56:57] op_sel_hi:[1,0,1]
	s_cmpk_lg_i32 s25, 0x400
	v_mov_b32_e32 v43, v37
	v_pk_add_f32 v[36:37], v[42:43], v[40:41]
	ds_read_b128 v[40:43], v39 offset:64
	ds_read_b128 v[44:47], v39 offset:80
	ds_read_b128 v[48:51], v39 offset:96
	ds_read_b128 v[52:55], v39 offset:112
	v_pk_mul_f32 v[56:57], v[34:35], v[36:37] op_sel:[0,1]
	s_waitcnt lgkmcnt(3)
	v_pk_fma_f32 v[58:59], v[2:3], v[40:41], 0 op_sel_hi:[1,0,0]
	v_pk_fma_f32 v[40:41], v[4:5], v[40:41], 0 op_sel:[0,1,0] op_sel_hi:[1,1,0]
	v_pk_fma_f32 v[58:59], v[6:7], v[42:43], v[58:59] op_sel_hi:[1,0,1]
	v_pk_fma_f32 v[40:41], v[8:9], v[42:43], v[40:41] op_sel:[0,1,0]
	s_waitcnt lgkmcnt(2)
	v_pk_fma_f32 v[42:43], v[10:11], v[44:45], v[58:59] op_sel_hi:[1,0,1]
	v_pk_fma_f32 v[40:41], v[12:13], v[44:45], v[40:41] op_sel:[0,1,0]
	v_pk_fma_f32 v[42:43], v[14:15], v[46:47], v[42:43] op_sel_hi:[1,0,1]
	v_pk_fma_f32 v[40:41], v[16:17], v[46:47], v[40:41] op_sel:[0,1,0]
	s_waitcnt lgkmcnt(1)
	v_pk_fma_f32 v[42:43], v[18:19], v[48:49], v[42:43] op_sel_hi:[1,0,1]
	v_pk_fma_f32 v[40:41], v[20:21], v[48:49], v[40:41] op_sel:[0,1,0]
	v_pk_fma_f32 v[42:43], v[22:23], v[50:51], v[42:43] op_sel_hi:[1,0,1]
	v_pk_fma_f32 v[40:41], v[24:25], v[50:51], v[40:41] op_sel:[0,1,0]
	s_waitcnt lgkmcnt(0)
	v_pk_fma_f32 v[42:43], v[26:27], v[52:53], v[42:43] op_sel_hi:[1,0,1]
	v_pk_fma_f32 v[40:41], v[28:29], v[52:53], v[40:41] op_sel:[0,1,0]
	v_pk_fma_f32 v[42:43], v[30:31], v[54:55], v[42:43] op_sel_hi:[1,0,1]
	v_pk_fma_f32 v[40:41], v[32:33], v[54:55], v[40:41] op_sel:[0,1,0]
	s_nop 0
	v_pk_add_f32 v[40:41], v[42:43], v[40:41]
	v_pk_fma_f32 v[42:43], v[0:1], v[36:37], v[56:57] neg_lo:[0,0,1] neg_hi:[0,0,1]
	v_pk_fma_f32 v[36:37], v[0:1], v[36:37], v[56:57] op_sel_hi:[1,0,1]
	s_nop 0
	v_mov_b32_e32 v43, v37
	v_pk_add_f32 v[36:37], v[42:43], v[40:41]
	s_cbranch_scc1 .LBB0_172
	s_add_i32 s5, s5, 1
	s_addk_i32 s24, 0x400
	s_cmp_lg_u32 s5, 4
	s_cbranch_scc1 .LBB0_171
	s_ashr_i32 s5, s4, 31
	s_lshl_b64 s[4:5], s[4:5], 17
	s_add_u32 s4, s43, s4
	s_addc_u32 s5, s46, s5
	s_lshl_b32 s3, s3, 9
	s_add_u32 s4, s4, s3
	s_addc_u32 s5, s5, 0
	s_add_i32 s2, s2, s68
	v_lshlrev_b32_e32 v0, 2, v38
	s_cmpk_gt_i32 s2, 0xfff
	global_store_dword v0, v36, s[4:5]
	global_store_dword v0, v37, s[4:5] offset:256
	s_cbranch_scc0 .LBB0_170
